# v25 + NSA bias-table fill de-serialised (five loads in flight, one wait)
# baseline (speedup 1.0000x reference)
; #define LAS __attribute__((address_space(3)))
; __global__ void __launch_bounds__(NTHREADS, 2) fwd_kernel(Args a) {
;     ...
;         { const float* TAB = (const float*)(ws + WS_TAB); LAS float* tl = (LAS float*)(lds + NL_TAB); for (int i = tid; i < 8 * 320; i += NTHREADS) { const int hd = i / 320, d = i % 320 - 64; tl[i] = (d < 0) ? NEG : TAB[hd * 128 + min(d, 127)]; } }
.LBB0_865:
	s_or_b64 exec, exec, s[4:5]
	s_movk_i32 s1, 0xa00
	v_cmp_gt_i32_e32 vcc, s1, v214
	s_waitcnt vmcnt(0) lgkmcnt(0)
	s_barrier
	s_and_saveexec_b64 s[4:5], vcc
	s_cbranch_execz .LBB0_870
	s_add_u32 s6, s40, 0x3220000
	v_lshl_add_u32 v0, v214, 2, 0
	s_addc_u32 s7, s41, 0
	v_add_u32_e32 v0, 0x1d600, v0
	s_mov_b32 s1, 0x66666667
	v_mov_b32_e32 v1, v214
	v_mul_hi_i32 v2, v1, s1
	v_lshrrev_b32_e32 v3, 31, v2
	v_ashrrev_i32_e32 v2, 7, v2
	v_add_u32_e32 v2, v2, v3
	v_mul_i32_i24_e32 v3, 0x140, v2
	v_sub_u32_e32 v4, v1, v3
	v_cmp_lt_i32_e32 vcc, 63, v4
	v_mov_b32_e32 v10, 0xf149f2ca
	s_and_saveexec_b64 s[10:11], vcc
	v_subrev_u32_e32 v3, 64, v4
	v_min_u32_e32 v3, 0x7f, v3
	v_lshl_or_b32 v2, v2, 7, v3
	v_ashrrev_i32_e32 v3, 31, v2
	v_lshl_add_u64 v[2:3], v[2:3], 2, s[6:7]
	global_load_dword v10, v[2:3], off
	s_or_b64 exec, exec, s[10:11]
	v_add_u32_e32 v1, 512, v214
	v_mul_hi_i32 v2, v1, s1
	v_lshrrev_b32_e32 v3, 31, v2
	v_ashrrev_i32_e32 v2, 7, v2
	v_add_u32_e32 v2, v2, v3
	v_mul_i32_i24_e32 v3, 0x140, v2
	v_sub_u32_e32 v4, v1, v3
	v_cmp_lt_i32_e32 vcc, 63, v4
	v_mov_b32_e32 v11, 0xf149f2ca
	s_and_saveexec_b64 s[10:11], vcc
	v_subrev_u32_e32 v3, 64, v4
	v_min_u32_e32 v3, 0x7f, v3
	v_lshl_or_b32 v2, v2, 7, v3
	v_ashrrev_i32_e32 v3, 31, v2
	v_lshl_add_u64 v[2:3], v[2:3], 2, s[6:7]
	global_load_dword v11, v[2:3], off
	s_or_b64 exec, exec, s[10:11]
	v_add_u32_e32 v1, 1024, v214
	v_mul_hi_i32 v2, v1, s1
	v_lshrrev_b32_e32 v3, 31, v2
	v_ashrrev_i32_e32 v2, 7, v2
	v_add_u32_e32 v2, v2, v3
	v_mul_i32_i24_e32 v3, 0x140, v2
	v_sub_u32_e32 v4, v1, v3
	v_cmp_lt_i32_e32 vcc, 63, v4
	v_mov_b32_e32 v12, 0xf149f2ca
	s_and_saveexec_b64 s[10:11], vcc
	v_subrev_u32_e32 v3, 64, v4
	v_min_u32_e32 v3, 0x7f, v3
	v_lshl_or_b32 v2, v2, 7, v3
	v_ashrrev_i32_e32 v3, 31, v2
	v_lshl_add_u64 v[2:3], v[2:3], 2, s[6:7]
	global_load_dword v12, v[2:3], off
	s_or_b64 exec, exec, s[10:11]
	v_add_u32_e32 v1, 1536, v214
	v_mul_hi_i32 v2, v1, s1
	v_lshrrev_b32_e32 v3, 31, v2
	v_ashrrev_i32_e32 v2, 7, v2
	v_add_u32_e32 v2, v2, v3
	v_mul_i32_i24_e32 v3, 0x140, v2
	v_sub_u32_e32 v4, v1, v3
	v_cmp_lt_i32_e32 vcc, 63, v4
	v_mov_b32_e32 v13, 0xf149f2ca
	s_and_saveexec_b64 s[10:11], vcc
	v_subrev_u32_e32 v3, 64, v4
	v_min_u32_e32 v3, 0x7f, v3
	v_lshl_or_b32 v2, v2, 7, v3
	v_ashrrev_i32_e32 v3, 31, v2
	v_lshl_add_u64 v[2:3], v[2:3], 2, s[6:7]
	global_load_dword v13, v[2:3], off
	s_or_b64 exec, exec, s[10:11]
	v_add_u32_e32 v1, 2048, v214
	v_mul_hi_i32 v2, v1, s1
	v_lshrrev_b32_e32 v3, 31, v2
	v_ashrrev_i32_e32 v2, 7, v2
	v_add_u32_e32 v2, v2, v3
	v_mul_i32_i24_e32 v3, 0x140, v2
	v_sub_u32_e32 v4, v1, v3
	v_cmp_lt_i32_e32 vcc, 63, v4
	v_mov_b32_e32 v14, 0xf149f2ca
	s_and_saveexec_b64 s[10:11], vcc
	v_subrev_u32_e32 v3, 64, v4
	v_min_u32_e32 v3, 0x7f, v3
	v_lshl_or_b32 v2, v2, 7, v3
	v_ashrrev_i32_e32 v3, 31, v2
	v_lshl_add_u64 v[2:3], v[2:3], 2, s[6:7]
	global_load_dword v14, v[2:3], off
	s_or_b64 exec, exec, s[10:11]
	s_waitcnt vmcnt(0)
	ds_write_b32 v0, v10
	ds_write_b32 v0, v11 offset:2048
	ds_write_b32 v0, v12 offset:4096
	ds_write_b32 v0, v13 offset:6144
	ds_write_b32 v0, v14 offset:8192
